# v6 + bias table staged once per phase (items 2-4 reuse the LDS copy)
# speedup vs baseline: 1.0371x; 1.0037x over previous
; #define LAS __attribute__((address_space(3)))
; __device__ __forceinline__ void diff2_item(const Params& p, LAS unsigned char* lds, const int item, const float lam, const float lam_init) {
;     ...
;     LAS float* tab = (LAS float*)(lds + D2_TAB);
;     const int q0w = qb * 128 + qs * 32; const size_t tq = (size_t)b * 2048 + q0w + r;
;     __syncthreads();
;     for (int i = tid; i < 1345; i += 512) tab[i] = gtab[i + 2047 - 672];
; __global__ void __launch_bounds__(512, 2) mega_fwd(Params p) {
;     ...
;             if (G == 256) {
;                 const int x = bid & 7, j = bid >> 3;
;                 for (int i = 0; i < 4; ++i) diff2_item(p, lds, (x + 8 * (2 * i + (j >> 4))) * 16 + (j & 15), lam, lam_init);
;             } else
.LBB0_315:
	v_mov_b32_e32 v2, v204
	s_nop 0
	v_cmp_gt_i32_e32 vcc, s53, v2
	s_barrier
	s_and_saveexec_b64 s[6:7], vcc
	s_cmp_lg_u32 s20, 0
	s_cbranch_scc1 .LBB0_323
	s_cbranch_execz .LBB0_323
	v_max_i32_e32 v0, 0x341, v2
	v_sub_u32_e32 v0, v0, v2
	v_add_u32_e32 v0, 0x1ff, v0
	s_movk_i32 s10, 0x1ff
	v_cmp_lt_u32_e32 vcc, s10, v0
	s_mov_b64 s[18:19], -1
	v_mov_b32_e32 v4, v2
	s_and_saveexec_b64 s[10:11], vcc
	s_cbranch_execz .LBB0_320
	v_lshrrev_b32_e32 v0, 9, v0
	v_add_u32_e32 v0, 1, v0
	v_and_b32_e32 v6, 0xfffffe, v0
	v_add_u32_e32 v3, 0x200, v2
	v_readlane_b32 s18, v250, 12
	v_mov_b32_e32 v8, v6
	v_mov_b64_e32 v[4:5], v[2:3]
	v_lshl_add_u32 v7, v2, 2, s18
	s_mov_b64 s[18:19], 0
